# t15 + score waves write each P fragment to LDS as soon as its permlane swaps are done (LDS write latency overlaps the remaining softmax VALU)
# speedup vs baseline: 1.0213x; 1.0005x over previous
; #define RS_BAR() do { asm volatile("s_waitcnt lgkmcnt(0)" ::: "memory"); __builtin_amdgcn_s_barrier(); asm volatile("" ::: "memory"); } while (0)
; #define KDMA(t, kb) do { _Pragma("unroll") for (int i = 0; i < 4; ++i) \
;       __builtin_amdgcn_global_load_lds((const unsigned*)(Kc + (long)(t) * 8192 + kdo[i]), (ATT_LAS unsigned*)(lds + RS_K + (kb) * 16384 + (pw * 4 + i) * 1024), 16, 0, 0); } while (0)
; #define VM0() asm volatile("s_waitcnt vmcnt(0)" ::: "memory")
; #define VM0() asm volatile("s_waitcnt vmcnt(0)" ::: "memory")
; __device__ __forceinline__ void partialSM(f32x16& p0, f32x16& p1, float& m_reg, float& mn, float& alpha) {
;     ...
;   float pmax = p0[0];
; #pragma unroll
;   for (int r = 1; r < 16; ++r) pmax = fmaxf(pmax, p0[r]);
; #pragma unroll
;   for (int r = 0; r < 16; ++r) pmax = fmaxf(pmax, p1[r]);
;   { auto rr = __builtin_amdgcn_permlane32_swap(__float_as_uint(pmax), __float_as_uint(pmax), false, false);
;     pmax = fmaxf(__uint_as_float(rr[0]), __uint_as_float(rr[1])); }
;   if (__builtin_expect(__all(pmax - m_reg <= THR / SCALE), 1)) { mn = m_reg; alpha = 1.f; }
;   else { mn = fmaxf(m_reg, pmax); alpha = __builtin_amdgcn_exp2f((m_reg - mn) * C); m_reg = mn; }
;   float mnC = -mn * C;
; #pragma unroll
;   for (int r = 0; r < 16; ++r) p0[r] = fmaf(p0[r], C, mnC);
; #pragma unroll
;   for (int r = 0; r < 16; ++r) p1[r] = fmaf(p1[r], C, mnC);
; #pragma unroll
;   for (int r = 0; r < 16; ++r) p0[r] = __builtin_amdgcn_exp2f(p0[r]);
; }
; __device__ __forceinline__ void finishSM(f32x16& p0, f32x16& p1, float alpha, float& l_reg, bf16x8& pa0, bf16x8& pa1, bf16x8& pa2, bf16x8& pa3) {
; #pragma unroll
;   for (int r = 0; r < 16; ++r) p1[r] = __builtin_amdgcn_exp2f(p1[r]);
;   float ps = 0;
; #pragma unroll
;   for (int r = 0; r < 16; ++r) ps += p0[r];
; template <class Epi>
; __device__ __forceinline__ void attn_rs_body(const bf16* __restrict__ Qb, const bf16* __restrict__ Kc, const bf16* __restrict__ V0c, const bf16* __restrict__ V1c, int NT, char* lds, const Epi& epi) {
;     ...
;     float m_reg = -1e30f, l_reg = 0.f;
;     f32x16 pA0, pA1, pB0, pB1;
;     KDMA(0, 0); KDMA(1, 1); VM0();
;     RS_BAR();
;     QKT_PF(pA0, pA1, 0);
;     RS_BAR();
.LBB0_508:
	s_cmpk_gt_u32 s71, 0x7d
	s_cselect_b64 s[48:49], -1, 0
	s_add_i32 s8, s72, 0xffffe000
	s_cmpk_lt_u32 s71, 0x7e
	s_cselect_b32 s8, s8, 0xfe000
	s_lshl_b64 s[84:85], s[8:9], 1
	s_add_u32 s84, s46, s84
	s_addc_u32 s85, s47, s85
	ds_read_b128 v[200:203], v108
	ds_read_b128 v[204:207], v108 offset:8192
	ds_read_b128 v[208:211], v109
	ds_read_b128 v[212:215], v109 offset:8192
	ds_read_b128 v[216:219], v110
	ds_read_b128 v[220:223], v110 offset:8192
	ds_read_b128 v[224:227], v111
	ds_read_b128 v[228:231], v111 offset:8192
	s_mov_b32 m0, s64
	s_nop 0
	global_load_lds_dwordx4 v0, s[84:85]
	s_mov_b32 m0, s2
	s_nop 0
	global_load_lds_dwordx4 v236, s[84:85]
	s_mov_b32 m0, s3
	s_nop 0
	global_load_lds_dwordx4 v237, s[84:85]
	s_mov_b32 m0, s66
	s_nop 0
	global_load_lds_dwordx4 v238, s[84:85]
	v_max_f32_e32 v99, v19, v19
	v_max_f32_e32 v118, v18, v18
	v_max_f32_e32 v99, v118, v99
	v_max3_f32 v99, v99, v20, v21
	v_max3_f32 v99, v99, v22, v23
	v_max3_f32 v99, v99, v24, v25
	v_max3_f32 v99, v99, v26, v27
	v_max3_f32 v99, v99, v28, v29
	v_max3_f32 v99, v99, v30, v31
	v_max3_f32 v99, v99, v32, v33
	s_waitcnt lgkmcnt(6)
	v_mfma_f32_32x32x16_bf16 v[50:65], v[200:203], v[66:69], 0
	v_max3_f32 v99, v99, v2, v3
	v_max3_f32 v99, v99, v4, v5
	v_max3_f32 v99, v99, v6, v7
	v_max3_f32 v99, v99, v8, v9
	v_max3_f32 v99, v99, v10, v11
	v_max3_f32 v99, v99, v12, v13
	v_max3_f32 v99, v99, v14, v15
	v_max3_f32 v99, v99, v16, v17
	v_mov_b32_e32 v118, v99
	v_mfma_f32_32x32x16_bf16 v[34:49], v[204:207], v[66:69], 0
	ds_read_b128 v[200:203], v113
	ds_read_b128 v[204:207], v113 offset:8192
	s_nop 1
	v_permlane32_swap_b32_e32 v99, v118
	v_max_f32_e32 v118, v118, v118
	v_max_f32_e32 v99, v99, v99
	v_max_f32_e32 v99, v99, v118
	v_sub_f32_e32 v118, v99, v121
	v_cmp_ge_f32_e32 vcc, s61, v118
	v_max_f32_e32 v119, v121, v121
	s_cmp_eq_u64 vcc, exec
	v_max_f32_e32 v99, v119, v99
	s_cselect_b64 vcc, -1, 0
	s_waitcnt lgkmcnt(6)
	v_mfma_f32_32x32x16_bf16 v[50:65], v[208:211], v[70:73], v[50:65]
	v_sub_f32_e32 v119, v121, v99
	v_cndmask_b32_e32 v121, v99, v121, vcc
	v_mul_f32_e32 v99, 0xbe0293ee, v121
	v_fmamk_f32 v18, v18, 0x3e0293ee, v99
	v_fmamk_f32 v19, v19, 0x3e0293ee, v99
	v_fmamk_f32 v20, v20, 0x3e0293ee, v99
	v_fmamk_f32 v21, v21, 0x3e0293ee, v99
	v_fmamk_f32 v22, v22, 0x3e0293ee, v99
	v_mfma_f32_32x32x16_bf16 v[34:49], v[212:215], v[70:73], v[34:49]
	ds_read_b128 v[208:211], v114
	ds_read_b128 v[212:215], v114 offset:8192
	v_fmamk_f32 v23, v23, 0x3e0293ee, v99
	v_fmamk_f32 v24, v24, 0x3e0293ee, v99
	v_fmamk_f32 v25, v25, 0x3e0293ee, v99
	v_fmamk_f32 v26, v26, 0x3e0293ee, v99
	v_fmamk_f32 v27, v27, 0x3e0293ee, v99
	v_fmamk_f32 v28, v28, 0x3e0293ee, v99
	v_fmamk_f32 v29, v29, 0x3e0293ee, v99
	v_fmamk_f32 v30, v30, 0x3e0293ee, v99
	v_fmamk_f32 v31, v31, 0x3e0293ee, v99
	s_waitcnt lgkmcnt(6)
	v_mfma_f32_32x32x16_bf16 v[50:65], v[216:219], v[74:77], v[50:65]
	v_fmamk_f32 v32, v32, 0x3e0293ee, v99
	v_fmamk_f32 v33, v33, 0x3e0293ee, v99
	v_fmamk_f32 v2, v2, 0x3e0293ee, v99
	v_fmamk_f32 v3, v3, 0x3e0293ee, v99
	v_fmamk_f32 v4, v4, 0x3e0293ee, v99
	v_fmamk_f32 v5, v5, 0x3e0293ee, v99
	v_fmamk_f32 v6, v6, 0x3e0293ee, v99
	v_fmamk_f32 v7, v7, 0x3e0293ee, v99
	v_fmamk_f32 v8, v8, 0x3e0293ee, v99
	v_mfma_f32_32x32x16_bf16 v[34:49], v[220:223], v[74:77], v[34:49]
	ds_read_b128 v[216:219], v115
	ds_read_b128 v[220:223], v115 offset:8192
	v_fmamk_f32 v9, v9, 0x3e0293ee, v99
	v_fmamk_f32 v10, v10, 0x3e0293ee, v99
	v_fmamk_f32 v11, v11, 0x3e0293ee, v99
	v_fmamk_f32 v12, v12, 0x3e0293ee, v99
	v_fmamk_f32 v13, v13, 0x3e0293ee, v99
	v_fmamk_f32 v14, v14, 0x3e0293ee, v99
	v_fmamk_f32 v15, v15, 0x3e0293ee, v99
	v_fmamk_f32 v16, v16, 0x3e0293ee, v99
	v_fmac_f32_e32 v99, 0x3e0293ee, v17
	v_exp_f32_e32 v17, v18
	s_waitcnt lgkmcnt(6)
	v_mfma_f32_32x32x16_bf16 v[50:65], v[224:227], v[78:81], v[50:65]
	v_exp_f32_e32 v18, v19
	v_exp_f32_e32 v19, v20
	v_exp_f32_e32 v20, v21
	v_exp_f32_e32 v21, v22
	v_exp_f32_e32 v22, v23
	v_exp_f32_e32 v23, v24
	v_exp_f32_e32 v24, v25
	v_exp_f32_e32 v25, v26
	v_exp_f32_e32 v26, v27
	v_mfma_f32_32x32x16_bf16 v[34:49], v[228:231], v[78:81], v[34:49]
	ds_read_b128 v[224:227], v116
	ds_read_b128 v[228:231], v116 offset:8192
	v_exp_f32_e32 v27, v28
	v_exp_f32_e32 v28, v29
	v_exp_f32_e32 v29, v30
	v_exp_f32_e32 v30, v31
	v_exp_f32_e32 v31, v32
	v_exp_f32_e32 v32, v33
	v_exp_f32_e32 v33, v2
	v_add_f32_e32 v2, 0, v17
	v_add_f32_e32 v2, v18, v2
	s_waitcnt lgkmcnt(6)
	v_mfma_f32_32x32x16_bf16 v[50:65], v[200:203], v[82:85], v[50:65]
	v_add_f32_e32 v2, v19, v2
	v_add_f32_e32 v2, v20, v2
	v_add_f32_e32 v2, v21, v2
	v_add_f32_e32 v2, v22, v2
	v_add_f32_e32 v2, v23, v2
	v_add_f32_e32 v2, v24, v2
	v_add_f32_e32 v2, v25, v2
	v_add_f32_e32 v2, v26, v2
	v_add_f32_e32 v2, v27, v2
	v_add_f32_e32 v2, v28, v2
	v_mfma_f32_32x32x16_bf16 v[34:49], v[204:207], v[82:85], v[34:49]
	v_add_f32_e32 v2, v29, v2
	v_exp_f32_e32 v122, v3
	v_add_f32_e32 v2, v30, v2
	v_exp_f32_e32 v123, v4
	v_add_f32_e32 v2, v31, v2
	v_exp_f32_e32 v124, v5
	v_add_f32_e32 v2, v32, v2
	v_exp_f32_e32 v125, v6
	v_add_f32_e32 v2, v33, v2
	s_waitcnt lgkmcnt(4)
	v_mfma_f32_32x32x16_bf16 v[50:65], v[208:211], v[86:89], v[50:65]
	v_exp_f32_e32 v126, v7
	v_add_f32_e32 v2, v122, v2
	v_exp_f32_e32 v127, v8
	v_add_f32_e32 v2, v123, v2
	v_exp_f32_e32 v128, v9
	v_add_f32_e32 v2, v124, v2
	v_exp_f32_e32 v129, v10
	v_add_f32_e32 v2, v125, v2
	v_exp_f32_e32 v130, v11
	v_mfma_f32_32x32x16_bf16 v[34:49], v[212:215], v[86:89], v[34:49]
	v_add_f32_e32 v2, v126, v2
	v_exp_f32_e32 v131, v12
	v_add_f32_e32 v2, v127, v2
	v_exp_f32_e32 v132, v13
	v_add_f32_e32 v2, v128, v2
	v_mul_f32_e32 v119, 0x3e0293ee, v119
	v_exp_f32_e32 v133, v14
	v_add_f32_e32 v2, v129, v2
	v_exp_f32_e32 v119, v119
	v_exp_f32_e32 v134, v15
	s_waitcnt lgkmcnt(2)
; __device__ __forceinline__ void finishSM(f32x16& p0, f32x16& p1, float alpha, float& l_reg, bf16x8& pa0, bf16x8& pa1, bf16x8& pa2, bf16x8& pa3) {
;     ...
;   { auto rr = __builtin_amdgcn_permlane32_swap(__float_as_uint(ps), __float_as_uint(ps), false, false);
;     ps = __uint_as_float(rr[0]) + __uint_as_float(rr[1]); }
;   l_reg = l_reg * alpha + ps;
;     ...
;   PK4(p0, 0, pa0); PK4(p0, 8, pa1); PK4(p1, 0, pa2); PK4(p1, 8, pa3);
	v_mfma_f32_32x32x16_bf16 v[50:65], v[216:219], v[90:93], v[50:65]
	v_add_f32_e32 v2, v130, v2
	v_exp_f32_e32 v135, v16
	v_add_f32_e32 v2, v131, v2
	v_exp_f32_e32 v99, v99
	v_add_f32_e32 v2, v132, v2
	v_add_f32_e32 v2, v133, v2
	v_cndmask_b32_e64 v118, v119, 1.0, vcc
	v_add_f32_e32 v2, v134, v2
	v_add_f32_e32 v2, v135, v2
	v_mfma_f32_32x32x16_bf16 v[34:49], v[220:223], v[90:93], v[34:49]
	v_cmp_gt_f32_e32 vcc, 1.0, v118
	v_add_f32_e32 v119, v99, v2
	s_cmp_lg_u64 vcc, 0
	v_mov_b32_e32 v120, v119
	v_cvt_pk_bf16_f32 v2, v17, v18
	v_cvt_pk_bf16_f32 v3, v19, v20
	v_cvt_pk_bf16_f32 v4, v21, v22
	v_cvt_pk_bf16_f32 v5, v23, v24
	s_cselect_b64 s[50:51], -1, 0
	s_waitcnt lgkmcnt(0)
	v_mfma_f32_32x32x16_bf16 v[50:65], v[224:227], v[94:97], v[50:65]
	s_nop 0
	v_permlane32_swap_b32_e32 v119, v120
	v_permlane32_swap_b32_e32 v2, v4
	v_permlane32_swap_b32_e32 v3, v5
	ds_write_b128 v179, v[2:5]
	v_cvt_pk_bf16_f32 v6, v25, v26
	v_cvt_pk_bf16_f32 v7, v27, v28
	v_cvt_pk_bf16_f32 v8, v29, v30
	v_cvt_pk_bf16_f32 v9, v31, v32
	v_cvt_pk_bf16_f32 v10, v33, v122
	v_cvt_pk_bf16_f32 v11, v123, v124
	v_mfma_f32_32x32x16_bf16 v[34:49], v[228:231], v[94:97], v[34:49]
	v_cvt_pk_bf16_f32 v12, v125, v126
	v_cvt_pk_bf16_f32 v13, v127, v128
	v_cvt_pk_bf16_f32 v14, v129, v130
	v_cvt_pk_bf16_f32 v15, v131, v132
	v_cvt_pk_bf16_f32 v16, v133, v134
	v_cvt_pk_bf16_f32 v17, v135, v99
	s_and_b64 s[74:75], s[50:51], s[0:1]
	v_permlane32_swap_b32_e32 v6, v8
	v_permlane32_swap_b32_e32 v7, v9
	ds_write_b128 v179, v[6:9] offset:1024
	v_permlane32_swap_b32_e32 v10, v12
	v_permlane32_swap_b32_e32 v11, v13
	ds_write_b128 v179, v[10:13] offset:2048
	v_permlane32_swap_b32_e32 v14, v16
	v_permlane32_swap_b32_e32 v15, v17
	ds_write_b128 v179, v[14:17] offset:3072
	s_and_saveexec_b64 s[52:53], s[74:75]
	ds_write_b32 v117, v118
	s_or_b64 exec, exec, s[52:53]
	s_and_saveexec_b64 s[52:53], s[4:5]
	v_cndmask_b32_e64 v2, 0, 1.0, s[50:51]
	v_mov_b32_e32 v3, s65
	ds_write_b32 v3, v2 offset:128
	s_or_b64 exec, exec, s[52:53]
	s_waitcnt vmcnt(0)
	s_waitcnt lgkmcnt(0)
	s_barrier
	s_cmpk_lt_u32 s71, 0x7d
	s_cselect_b32 s8, s72, 0xfe000
	s_lshl_b64 s[84:85], s[8:9], 1
	s_add_u32 s84, s46, s84
	s_addc_u32 s85, s47, s85
	ds_read_b128 v[200:203], v100
	ds_read_b128 v[204:207], v100 offset:8192
	ds_read_b128 v[208:211], v101
	ds_read_b128 v[212:215], v101 offset:8192
	ds_read_b128 v[216:219], v102
	ds_read_b128 v[220:223], v102 offset:8192
	ds_read_b128 v[224:227], v103
	ds_read_b128 v[228:231], v103 offset:8192
	s_mov_b32 m0, s67
	s_nop 0
	global_load_lds_dwordx4 v0, s[84:85]
	s_mov_b32 m0, s68
	s_nop 0
	global_load_lds_dwordx4 v236, s[84:85]
	s_mov_b32 m0, s69
	s_nop 0
	global_load_lds_dwordx4 v237, s[84:85]
	s_mov_b32 m0, s70
	s_nop 0
	global_load_lds_dwordx4 v238, s[84:85]
	v_max_f32_e32 v99, v51, v51
	v_max_f32_e32 v122, v50, v50
	v_max_f32_e32 v99, v122, v99
	v_max3_f32 v99, v99, v52, v53
	v_max3_f32 v99, v99, v54, v55
	v_max3_f32 v99, v99, v56, v57
	v_max3_f32 v99, v99, v58, v59
	v_max3_f32 v99, v99, v60, v61
	v_max3_f32 v99, v99, v62, v63
	v_max3_f32 v99, v99, v64, v65
	s_waitcnt lgkmcnt(6)
	v_mfma_f32_32x32x16_bf16 v[18:33], v[200:203], v[66:69], 0
	v_max3_f32 v99, v99, v34, v35
	v_max3_f32 v99, v99, v36, v37
	v_max3_f32 v99, v99, v38, v39
	v_max3_f32 v99, v99, v40, v41
	v_max3_f32 v99, v99, v42, v43
	v_max3_f32 v99, v99, v44, v45
	v_max3_f32 v99, v99, v46, v47
	v_max3_f32 v99, v99, v48, v49
	v_mov_b32_e32 v122, v99
	v_mfma_f32_32x32x16_bf16 v[2:17], v[204:207], v[66:69], 0
	ds_read_b128 v[200:203], v104
	ds_read_b128 v[204:207], v104 offset:8192
	s_nop 1
	v_permlane32_swap_b32_e32 v99, v122
	v_max_f32_e32 v122, v122, v122
	v_max_f32_e32 v99, v99, v99
	v_max_f32_e32 v99, v99, v122
	v_sub_f32_e32 v122, v99, v121
	v_cmp_ge_f32_e32 vcc, s61, v122
	v_max_f32_e32 v123, v121, v121
	s_cmp_eq_u64 vcc, exec
	v_max_f32_e32 v123, v123, v99
	s_cselect_b64 vcc, -1, 0
	s_waitcnt lgkmcnt(6)
	v_mfma_f32_32x32x16_bf16 v[18:33], v[208:211], v[70:73], v[18:33]
	v_sub_f32_e32 v99, v121, v123
	v_cndmask_b32_e32 v121, v123, v121, vcc
	v_mul_f32_e32 v122, 0xbe0293ee, v121
	v_fmamk_f32 v50, v50, 0x3e0293ee, v122
	v_fmamk_f32 v51, v51, 0x3e0293ee, v122
	v_fmamk_f32 v52, v52, 0x3e0293ee, v122
	v_fmamk_f32 v53, v53, 0x3e0293ee, v122
	v_fmamk_f32 v54, v54, 0x3e0293ee, v122
	v_mfma_f32_32x32x16_bf16 v[2:17], v[212:215], v[70:73], v[2:17]
	ds_read_b128 v[208:211], v105
	ds_read_b128 v[212:215], v105 offset:8192
	v_fmamk_f32 v55, v55, 0x3e0293ee, v122
	v_fmamk_f32 v56, v56, 0x3e0293ee, v122
	v_fmamk_f32 v57, v57, 0x3e0293ee, v122
	v_fmamk_f32 v58, v58, 0x3e0293ee, v122
	v_fmamk_f32 v59, v59, 0x3e0293ee, v122
	v_fmamk_f32 v60, v60, 0x3e0293ee, v122
	v_fmamk_f32 v61, v61, 0x3e0293ee, v122
	v_fmamk_f32 v62, v62, 0x3e0293ee, v122
	v_fmamk_f32 v63, v63, 0x3e0293ee, v122
	s_waitcnt lgkmcnt(6)
; __device__ __forceinline__ void finishSM(f32x16& p0, f32x16& p1, float alpha, float& l_reg, bf16x8& pa0, bf16x8& pa1, bf16x8& pa2, bf16x8& pa3) {
; #pragma unroll
;   for (int r = 0; r < 16; ++r) p1[r] = __builtin_amdgcn_exp2f(p1[r]);
;   float ps = 0;
; #pragma unroll
;   for (int r = 0; r < 16; ++r) ps += p0[r];
; #pragma unroll
;   for (int r = 0; r < 16; ++r) ps += p1[r];
;   { auto rr = __builtin_amdgcn_permlane32_swap(__float_as_uint(ps), __float_as_uint(ps), false, false);
;     ps = __uint_as_float(rr[0]) + __uint_as_float(rr[1]); }
;   l_reg = l_reg * alpha + ps;
;     ...
;   PK4(p0, 0, pa0); PK4(p0, 8, pa1); PK4(p1, 0, pa2); PK4(p1, 8, pa3);
	v_mfma_f32_32x32x16_bf16 v[18:33], v[216:219], v[74:77], v[18:33]
	v_fmamk_f32 v64, v64, 0x3e0293ee, v122
	v_fmamk_f32 v65, v65, 0x3e0293ee, v122
	v_fmamk_f32 v34, v34, 0x3e0293ee, v122
	v_fmamk_f32 v35, v35, 0x3e0293ee, v122
	v_fmamk_f32 v36, v36, 0x3e0293ee, v122
	v_fmamk_f32 v37, v37, 0x3e0293ee, v122
	v_fmamk_f32 v38, v38, 0x3e0293ee, v122
	v_fmamk_f32 v39, v39, 0x3e0293ee, v122
	v_fmamk_f32 v40, v40, 0x3e0293ee, v122
	v_mfma_f32_32x32x16_bf16 v[2:17], v[220:223], v[74:77], v[2:17]
	ds_read_b128 v[216:219], v106
	ds_read_b128 v[220:223], v106 offset:8192
	v_fmamk_f32 v41, v41, 0x3e0293ee, v122
	v_fmamk_f32 v42, v42, 0x3e0293ee, v122
	v_fmamk_f32 v43, v43, 0x3e0293ee, v122
	v_fmamk_f32 v44, v44, 0x3e0293ee, v122
	v_fmamk_f32 v45, v45, 0x3e0293ee, v122
	v_fmamk_f32 v46, v46, 0x3e0293ee, v122
	v_fmamk_f32 v47, v47, 0x3e0293ee, v122
	v_fmamk_f32 v48, v48, 0x3e0293ee, v122
	v_fmac_f32_e32 v122, 0x3e0293ee, v49
	v_exp_f32_e32 v49, v50
	s_waitcnt lgkmcnt(6)
	v_mfma_f32_32x32x16_bf16 v[18:33], v[224:227], v[78:81], v[18:33]
	v_exp_f32_e32 v50, v51
	v_exp_f32_e32 v51, v52
	v_exp_f32_e32 v52, v53
	v_exp_f32_e32 v53, v54
	v_exp_f32_e32 v54, v55
	v_exp_f32_e32 v55, v56
	v_exp_f32_e32 v56, v57
	v_exp_f32_e32 v57, v58
	v_exp_f32_e32 v58, v59
	v_mfma_f32_32x32x16_bf16 v[2:17], v[228:231], v[78:81], v[2:17]
	ds_read_b128 v[224:227], v107
	ds_read_b128 v[228:231], v107 offset:8192
	v_exp_f32_e32 v59, v60
	v_exp_f32_e32 v60, v61
	v_exp_f32_e32 v61, v62
	v_exp_f32_e32 v62, v63
	v_exp_f32_e32 v63, v64
	v_exp_f32_e32 v64, v65
	v_exp_f32_e32 v65, v34
	v_add_f32_e32 v34, 0, v49
	v_add_f32_e32 v34, v50, v34
	s_waitcnt lgkmcnt(6)
	v_mfma_f32_32x32x16_bf16 v[18:33], v[200:203], v[82:85], v[18:33]
	v_add_f32_e32 v34, v51, v34
	v_add_f32_e32 v34, v52, v34
	v_add_f32_e32 v34, v53, v34
	v_add_f32_e32 v34, v54, v34
	v_add_f32_e32 v34, v55, v34
	v_add_f32_e32 v34, v56, v34
	v_add_f32_e32 v34, v57, v34
	v_add_f32_e32 v34, v58, v34
	v_add_f32_e32 v34, v59, v34
	v_add_f32_e32 v34, v60, v34
	v_mfma_f32_32x32x16_bf16 v[2:17], v[204:207], v[82:85], v[2:17]
	v_add_f32_e32 v34, v61, v34
	v_exp_f32_e32 v123, v35
	v_add_f32_e32 v34, v62, v34
	v_exp_f32_e32 v124, v36
	v_add_f32_e32 v34, v63, v34
	v_exp_f32_e32 v125, v37
	v_add_f32_e32 v34, v64, v34
	v_exp_f32_e32 v126, v38
	v_add_f32_e32 v34, v65, v34
	s_waitcnt lgkmcnt(4)
	v_mfma_f32_32x32x16_bf16 v[18:33], v[208:211], v[86:89], v[18:33]
	v_exp_f32_e32 v127, v39
	v_add_f32_e32 v34, v123, v34
	v_exp_f32_e32 v128, v40
	v_add_f32_e32 v34, v124, v34
	v_exp_f32_e32 v129, v41
	v_add_f32_e32 v34, v125, v34
	v_exp_f32_e32 v130, v42
	v_add_f32_e32 v34, v126, v34
	v_exp_f32_e32 v131, v43
	v_mfma_f32_32x32x16_bf16 v[2:17], v[212:215], v[86:89], v[2:17]
	v_add_f32_e32 v34, v127, v34
	v_exp_f32_e32 v132, v44
	v_add_f32_e32 v34, v128, v34
	v_exp_f32_e32 v133, v45
	v_add_f32_e32 v34, v129, v34
	v_mul_f32_e32 v99, 0x3e0293ee, v99
	v_exp_f32_e32 v134, v46
	v_add_f32_e32 v34, v130, v34
	v_exp_f32_e32 v99, v99
	v_exp_f32_e32 v135, v47
	s_waitcnt lgkmcnt(2)
	v_mfma_f32_32x32x16_bf16 v[18:33], v[216:219], v[90:93], v[18:33]
	v_add_f32_e32 v34, v131, v34
	v_exp_f32_e32 v136, v48
	v_add_f32_e32 v34, v132, v34
	v_exp_f32_e32 v122, v122
	v_add_f32_e32 v34, v133, v34
	v_add_f32_e32 v34, v134, v34
	v_cndmask_b32_e64 v99, v99, 1.0, vcc
	v_add_f32_e32 v34, v135, v34
	v_add_f32_e32 v34, v136, v34
	v_mfma_f32_32x32x16_bf16 v[2:17], v[220:223], v[90:93], v[2:17]
	v_cmp_gt_f32_e32 vcc, 1.0, v99
	v_add_f32_e32 v34, v122, v34
	s_cmp_lg_u64 vcc, 0
	v_mov_b32_e32 v35, v34
	v_cvt_pk_bf16_f32 v36, v49, v50
	v_cvt_pk_bf16_f32 v37, v51, v52
	v_cvt_pk_bf16_f32 v38, v53, v54
	v_cvt_pk_bf16_f32 v39, v55, v56
	s_cselect_b64 s[50:51], -1, 0
	s_waitcnt lgkmcnt(0)
	v_mfma_f32_32x32x16_bf16 v[18:33], v[224:227], v[94:97], v[18:33]
	s_nop 0
	v_permlane32_swap_b32_e32 v34, v35
	v_permlane32_swap_b32_e32 v36, v38
	v_permlane32_swap_b32_e32 v37, v39
	ds_write_b128 v179, v[36:39] offset:16384
	v_cvt_pk_bf16_f32 v40, v57, v58
	v_cvt_pk_bf16_f32 v41, v59, v60
	v_cvt_pk_bf16_f32 v42, v61, v62
	v_cvt_pk_bf16_f32 v43, v63, v64
	v_cvt_pk_bf16_f32 v44, v65, v123
	v_cvt_pk_bf16_f32 v45, v124, v125
	v_mfma_f32_32x32x16_bf16 v[2:17], v[228:231], v[94:97], v[2:17]
	v_cvt_pk_bf16_f32 v46, v126, v127
	v_cvt_pk_bf16_f32 v47, v128, v129
	v_cvt_pk_bf16_f32 v48, v130, v131
	v_cvt_pk_bf16_f32 v49, v132, v133
	v_cvt_pk_bf16_f32 v50, v134, v135
	v_cvt_pk_bf16_f32 v51, v136, v122
	s_and_b64 s[74:75], s[50:51], s[0:1]
	v_permlane32_swap_b32_e32 v40, v42
	v_permlane32_swap_b32_e32 v41, v43
	ds_write_b128 v179, v[40:43] offset:17408
	v_permlane32_swap_b32_e32 v44, v46
	v_permlane32_swap_b32_e32 v45, v47
	ds_write_b128 v179, v[44:47] offset:18432
	v_permlane32_swap_b32_e32 v48, v50
	v_permlane32_swap_b32_e32 v49, v51
	ds_write_b128 v179, v[48:51] offset:19456
	s_and_saveexec_b64 s[52:53], s[74:75]
	ds_write_b32 v117, v99 offset:1024
	s_or_b64 exec, exec, s[52:53]
	s_and_saveexec_b64 s[52:53], s[4:5]
	s_cbranch_execz .LBB0_507
	v_cndmask_b32_e64 v36, 0, 1.0, s[50:51]
	v_mov_b32_e32 v37, s65
	ds_write_b32 v37, v36 offset:1152
	s_branch .LBB0_507
